# attention row-sum: packed v_pk_add_f32 between MFMAs split into scalar adds (same order); on top of P10 newest-first, P1+P8 4x8 unit order, max tree, batched skinny loads
# speedup vs baseline: 1.0063x; 1.0063x over previous
; __device__ __forceinline__ unsigned cvtpk(float lo, float hi) { f32x2 v = {lo, hi}; bf16x2_t b = __builtin_convertvector(v, bf16x2_t); return __builtin_bit_cast(unsigned, b); }
; __device__ __forceinline__ s16x4 vtr(LAS const unsigned char* p) { typedef short v4i16_t __attribute__((ext_vector_type(4))); return __builtin_bit_cast(s16x4, __builtin_amdgcn_ds_read_tr16_b64_v4i16((LAS v4i16_t*)p)); }
; __device__ __forceinline__ void attn_unit(const bf16* __restrict__ QB, const bf16* __restrict__ KB, const bf16* __restrict__ VB, bf16* __restrict__ YATT, ...
;     ...
;             float ps = 0.f;
; #pragma unroll
;             for (int r = 0; r < 16; ++r) { s0[r] = __builtin_amdgcn_exp2f(s0[r]); s1[r] = __builtin_amdgcn_exp2f(s1[r]); ps += s0[r] + s1[r]; }
;             lrun += ps;
;             bf16x8 pf[4];
; #pragma unroll
;             for (int s = 0; s < 4; ++s) {
;                 u32x4 w;
;                 if (s < 2) { const int o = 8 * s; w.x = cvtpk(s0[o], s0[o + 1]); w.y = cvtpk(s0[o + 2], s0[o + 3]); w.z = cvtpk(s0[o + 4], s0[o + 5]); w.w = cvtpk(s0[o + 6], s0[o + 7]); }
;                 else { const int o = 8 * (s - 2); w.x = cvtpk(s1[o], s1[o + 1]); w.y = cvtpk(s1[o + 2], s1[o + 3]); w.z = cvtpk(s1[o + 4], s1[o + 5]); w.w = cvtpk(s1[o + 6], s1[o + 7]); }
;                 pf[s] = __builtin_bit_cast(bf16x8, w);
;             }
; #pragma unroll
;             for (int s = 0; s < 4; ++s) {
; #pragma unroll
;                 for (int e = 0; e < 4; ++e) {
;                     const s16x4 lo = vtr(Vc + s * 4096 + e * 512), hv = vtr(Vc + s * 4096 + e * 512 + 2048);
;                     const bf16x8 vf = (bf16x8){lo[0], lo[1], lo[2], lo[3], hv[0], hv[1], hv[2], hv[3]};
;                     acc[e] = __builtin_amdgcn_mfma_f32_32x32x16_bf16(vf, pf[s], acc[e], 0, 0, 0);
;                 }
;             }
.LBB0_579:
	v_exp_f32_e32 v10, v114
	v_exp_f32_e32 v151, v98
	v_exp_f32_e32 v4, v115
	v_exp_f32_e32 v2, v99
	v_exp_f32_e32 v155, v100
	v_add_f32_e32 v209, v151, v10
	v_exp_f32_e32 v114, v101
	v_add_f32_e32 v210, v2, v4
	v_exp_f32_e32 v3, v116
	v_add_f32_e32 v209, v210, v209
	v_exp_f32_e32 v8, v117
	v_exp_f32_e32 v116, v103
	v_add_f32_e32 v210, v155, v3
	v_exp_f32_e32 v208, v106
	v_add_f32_e32 v209, v210, v209
	v_add_f32_e32 v210, v114, v8
	v_exp_f32_e32 v9, v118
	v_add_f32_e32 v209, v210, v209
	v_exp_f32_e32 v115, v102
	v_exp_f32_e32 v14, v119
	v_exp_f32_e32 v118, v105
	v_exp_f32_e32 v106, v107
	v_add_f32_e32 v210, v115, v9
	v_add_f32_e32 v209, v210, v209
	v_add_f32_e32 v210, v116, v14
	v_exp_f32_e32 v15, v120
	v_add_f32_e32 v209, v210, v209
	v_exp_f32_e32 v117, v104
	v_exp_f32_e32 v16, v121
	v_add_f32_e32 v210, v117, v15
	v_add_f32_e32 v209, v210, v209
	v_add_f32_e32 v210, v118, v16
	v_exp_f32_e32 v119, v122
	v_add_f32_e32 v209, v210, v209
	v_exp_f32_e32 v120, v123
	v_add_f32_e32 v210, v208, v119
	v_add_f32_e32 v209, v210, v209
	v_add_f32_e32 v210, v106, v120
	s_nop 0
	v_add_f32_e32 v209, v210, v209
	v_cvt_pk_bf16_f32 v7, v3, v8
	v_lshl_add_u32 v3, s86, 14, v201
	v_exp_f32_e32 v107, v124
	v_exp_f32_e32 v121, v108
	v_cvt_pk_bf16_f32 v6, v10, v4
	ds_read_b64_tr_b16 v[10:11], v3 offset:36864
	ds_read_b64_tr_b16 v[12:13], v3 offset:38912
	v_exp_f32_e32 v122, v125
	v_exp_f32_e32 v108, v109
	v_cvt_pk_bf16_f32 v8, v9, v14
	v_cvt_pk_bf16_f32 v9, v15, v16
	v_add_f32_e32 v210, v121, v107
	ds_read_b64_tr_b16 v[14:15], v3 offset:37376
	ds_read_b64_tr_b16 v[98:99], v3 offset:37888
	ds_read_b64_tr_b16 v[102:103], v3 offset:38400
	ds_read_b64_tr_b16 v[16:17], v3 offset:39424
	ds_read_b64_tr_b16 v[100:101], v3 offset:39936
	ds_read_b64_tr_b16 v[104:105], v3 offset:40448
	s_waitcnt lgkmcnt(6)
	v_mfma_f32_32x32x16_bf16 v[66:81], v[10:13], v[6:9], v[66:81]
	v_add_f32_e32 v209, v210, v209
	v_add_f32_e32 v210, v108, v122
	v_exp_f32_e32 v4, v126
	v_add_f32_e32 v209, v210, v209
	v_exp_f32_e32 v109, v110
	v_exp_f32_e32 v12, v127
	v_exp_f32_e32 v110, v111
	v_add_f32_e32 v210, v109, v4
	s_waitcnt lgkmcnt(2)
	v_mfma_f32_32x32x16_bf16 v[50:65], v[14:17], v[6:9], v[50:65]
	v_add_f32_e32 v209, v210, v209
	v_add_f32_e32 v210, v110, v12
	v_exp_f32_e32 v111, v128
	v_add_f32_e32 v209, v210, v209
	v_exp_f32_e32 v124, v129
	ds_read_b64_tr_b16 v[14:15], v3 offset:40960
	ds_read_b64_tr_b16 v[16:17], v3 offset:43008
	v_cvt_pk_bf16_f32 v10, v119, v120
	v_cvt_pk_bf16_f32 v11, v107, v122
	s_waitcnt lgkmcnt(3)
	v_mfma_f32_32x32x16_bf16 v[34:49], v[98:101], v[6:9], v[34:49]
	v_cvt_pk_bf16_f32 v12, v4, v12
	v_cvt_pk_bf16_f32 v13, v111, v124
	v_exp_f32_e32 v4, v112
	s_waitcnt lgkmcnt(2)
	v_mfma_f32_32x32x16_bf16 v[18:33], v[102:105], v[6:9], v[18:33]
	ds_read_b64_tr_b16 v[6:7], v3 offset:41472
	ds_read_b64_tr_b16 v[98:99], v3 offset:41984
	ds_read_b64_tr_b16 v[102:103], v3 offset:42496
	ds_read_b64_tr_b16 v[8:9], v3 offset:43520
	ds_read_b64_tr_b16 v[100:101], v3 offset:44032
	ds_read_b64_tr_b16 v[104:105], v3 offset:44544
	s_waitcnt lgkmcnt(6)
	v_mfma_f32_32x32x16_bf16 v[66:81], v[14:17], v[10:13], v[66:81]
	ds_read_b64_tr_b16 v[14:15], v3 offset:45056
	ds_read_b64_tr_b16 v[16:17], v3 offset:47104
	s_waitcnt lgkmcnt(4)
	v_mfma_f32_32x32x16_bf16 v[50:65], v[6:9], v[10:13], v[50:65]
	v_cvt_pk_bf16_f32 v6, v151, v2
	v_cvt_pk_bf16_f32 v7, v155, v114
	v_cvt_pk_bf16_f32 v8, v115, v116
	v_cvt_pk_bf16_f32 v9, v117, v118
	v_exp_f32_e32 v2, v113
	s_waitcnt lgkmcnt(3)
	v_mfma_f32_32x32x16_bf16 v[34:49], v[98:101], v[10:13], v[34:49]
	s_waitcnt lgkmcnt(2)
	v_mfma_f32_32x32x16_bf16 v[18:33], v[102:105], v[10:13], v[18:33]
	ds_read_b64_tr_b16 v[10:11], v3 offset:45568
	ds_read_b64_tr_b16 v[98:99], v3 offset:46080
	ds_read_b64_tr_b16 v[102:103], v3 offset:46592
	ds_read_b64_tr_b16 v[12:13], v3 offset:47616
	ds_read_b64_tr_b16 v[100:101], v3 offset:48128
	ds_read_b64_tr_b16 v[104:105], v3 offset:48640
	s_waitcnt lgkmcnt(6)
	v_mfma_f32_32x32x16_bf16 v[66:81], v[14:17], v[6:9], v[66:81]
	ds_read_b64_tr_b16 v[14:15], v3 offset:49152
	ds_read_b64_tr_b16 v[16:17], v3 offset:51200
	s_waitcnt lgkmcnt(4)
	v_mfma_f32_32x32x16_bf16 v[50:65], v[10:13], v[6:9], v[50:65]
	v_cvt_pk_bf16_f32 v10, v208, v106
	v_cvt_pk_bf16_f32 v11, v121, v108
	v_cvt_pk_bf16_f32 v12, v109, v110
	v_cvt_pk_bf16_f32 v13, v4, v2
	s_waitcnt lgkmcnt(3)
	v_mfma_f32_32x32x16_bf16 v[34:49], v[98:101], v[6:9], v[34:49]
	s_waitcnt lgkmcnt(2)
	v_mfma_f32_32x32x16_bf16 v[18:33], v[102:105], v[6:9], v[18:33]
	ds_read_b64_tr_b16 v[6:7], v3 offset:49664
	ds_read_b64_tr_b16 v[98:99], v3 offset:50176
	ds_read_b64_tr_b16 v[102:103], v3 offset:50688
	ds_read_b64_tr_b16 v[8:9], v3 offset:51712
	ds_read_b64_tr_b16 v[100:101], v3 offset:52224
	ds_read_b64_tr_b16 v[104:105], v3 offset:52736
	v_add_f32_e32 v210, v4, v111
	v_add_f32_e32 v209, v210, v209
	v_add_f32_e32 v210, v2, v124
	s_nop 0
	v_add_f32_e32 v209, v210, v209
	v_add_f32_e32 v207, v207, v209
	s_waitcnt lgkmcnt(6)
	v_mfma_f32_32x32x16_bf16 v[66:81], v[14:17], v[10:13], v[66:81]
	s_waitcnt lgkmcnt(2)
	v_mfma_f32_32x32x16_bf16 v[50:65], v[6:9], v[10:13], v[50:65]
	s_waitcnt lgkmcnt(1)
	v_mfma_f32_32x32x16_bf16 v[34:49], v[98:101], v[10:13], v[34:49]
	s_waitcnt lgkmcnt(0)
	v_mfma_f32_32x32x16_bf16 v[18:33], v[102:105], v[10:13], v[18:33]
